# delete 7 compiler-artifact vmcnt(0) at GEMM unit starts
# speedup vs baseline: 1.0042x; 1.0042x over previous
.LBB0_697:
	s_and_b32 s29, s69, 0x1000
	s_add_i32 s70, s66, s29
	s_ashr_i32 s29, s28, 31
	ds_read_b128 v[0:3], v195 offset:3072
	ds_read_b128 v[4:7], v195 offset:2048
	ds_read_b128 v[8:11], v195 offset:1024
	ds_read_b128 v[12:15], v195
	ds_read_b128 v[16:19], v203 offset:3072
	ds_read_b128 v[20:23], v203 offset:2048
	ds_read_b128 v[24:27], v203 offset:1024
	ds_read_b128 v[28:31], v203
	s_lshl_b64 s[36:37], s[28:29], 20
	s_add_u32 s36, s50, s36
	s_addc_u32 s37, s51, s37
	s_and_b64 s[38:39], s[4:5], exec
	s_cselect_b32 s29, s37, s45
	s_cselect_b32 s71, s36, s44
	s_ashr_i32 s31, s30, 31
	s_lshl_b64 s[38:39], s[30:31], 20
	s_add_u32 s38, s54, s38
	s_addc_u32 s39, s55, s39
	s_and_b64 s[48:49], s[4:5], exec
	s_cselect_b32 s31, s39, s47
	s_cselect_b32 s72, s38, s46
	s_add_u32 s48, s44, 0x80080
	s_addc_u32 s49, s45, 0
	s_add_i32 s73, s56, 0xc000
	v_lshl_add_u64 v[64:65], s[48:49], 0, v[176:177]
	s_mov_b32 m0, s73
	s_add_i32 s74, s56, 0xe000
	ds_read_b128 v[32:35], v211
	ds_read_b128 v[36:39], v211 offset:1024
	ds_read_b128 v[40:43], v211 offset:2048
	ds_read_b128 v[44:47], v211 offset:3072
	ds_read_b128 v[48:51], v211 offset:4096
	ds_read_b128 v[52:55], v211 offset:5120
	ds_read_b128 v[56:59], v211 offset:6144
	ds_read_b128 v[60:63], v211 offset:7168
	global_load_lds_dwordx4 v[64:65], off
	v_lshl_add_u64 v[64:65], s[48:49], 0, v[178:179]
	s_mov_b32 m0, s74
	s_nop 0
	global_load_lds_dwordx4 v[64:65], off
	s_waitcnt vmcnt(8)
	s_waitcnt lgkmcnt(0)
	s_barrier
	s_setprio 1
	s_waitcnt lgkmcnt(0)
	v_mfma_f32_16x16x32_bf16 v[88:91], v[28:31], v[56:59], 0
	v_mfma_f32_16x16x32_bf16 v[64:67], v[28:31], v[32:35], 0
	v_mfma_f32_16x16x32_bf16 v[68:71], v[20:23], v[32:35], 0
	v_mfma_f32_16x16x32_bf16 v[72:75], v[28:31], v[40:43], 0
	v_mfma_f32_16x16x32_bf16 v[76:79], v[20:23], v[40:43], 0
	v_mfma_f32_16x16x32_bf16 v[80:83], v[28:31], v[48:51], 0
	v_mfma_f32_16x16x32_bf16 v[84:87], v[20:23], v[48:51], 0
	v_mfma_f32_16x16x32_bf16 v[96:99], v[24:27], v[60:63], v[88:91]
	v_mfma_f32_16x16x32_bf16 v[88:91], v[20:23], v[56:59], 0
	v_mfma_f32_16x16x32_bf16 v[64:67], v[24:27], v[36:39], v[64:67]
	v_mfma_f32_16x16x32_bf16 v[68:71], v[16:19], v[36:39], v[68:71]
	v_mfma_f32_16x16x32_bf16 v[72:75], v[24:27], v[44:47], v[72:75]
	v_mfma_f32_16x16x32_bf16 v[76:79], v[16:19], v[44:47], v[76:79]
	v_mfma_f32_16x16x32_bf16 v[80:83], v[24:27], v[52:55], v[80:83]
	v_mfma_f32_16x16x32_bf16 v[84:87], v[16:19], v[52:55], v[84:87]
	v_mfma_f32_16x16x32_bf16 v[100:103], v[16:19], v[60:63], v[88:91]
	s_setprio 0
	s_setprio 1
	v_mfma_f32_16x16x32_bf16 v[88:91], v[12:15], v[32:35], 0
	v_mfma_f32_16x16x32_bf16 v[32:35], v[4:7], v[32:35], 0
	v_mfma_f32_16x16x32_bf16 v[112:115], v[8:11], v[36:39], v[88:91]
	v_mfma_f32_16x16x32_bf16 v[32:35], v[0:3], v[36:39], v[32:35]
	v_mfma_f32_16x16x32_bf16 v[36:39], v[12:15], v[40:43], 0
	v_mfma_f32_16x16x32_bf16 v[40:43], v[4:7], v[40:43], 0
	v_mfma_f32_16x16x32_bf16 v[36:39], v[8:11], v[44:47], v[36:39]
	v_mfma_f32_16x16x32_bf16 v[40:43], v[0:3], v[44:47], v[40:43]
	v_mfma_f32_16x16x32_bf16 v[44:47], v[12:15], v[48:51], 0
	v_mfma_f32_16x16x32_bf16 v[48:51], v[4:7], v[48:51], 0
	v_mfma_f32_16x16x32_bf16 v[44:47], v[8:11], v[52:55], v[44:47]
	v_mfma_f32_16x16x32_bf16 v[48:51], v[0:3], v[52:55], v[48:51]
	v_mfma_f32_16x16x32_bf16 v[52:55], v[12:15], v[56:59], 0
	v_mfma_f32_16x16x32_bf16 v[56:59], v[4:7], v[56:59], 0
	v_mfma_f32_16x16x32_bf16 v[52:55], v[8:11], v[60:63], v[52:55]
	v_mfma_f32_16x16x32_bf16 v[56:59], v[0:3], v[60:63], v[56:59]
	s_setprio 0
	s_barrier
	s_add_i32 s75, s68, s43
	v_lshl_add_u64 v[174:175], s[46:47], 0, v[176:177]
	s_add_i32 s76, s75, 0x2000
	v_lshl_add_u64 v[128:129], v[174:175], 0, s[24:25]
	s_mov_b32 m0, s75
	v_lshl_add_u64 v[200:201], s[46:47], 0, v[178:179]
	s_add_u32 s48, s46, 0x80100
	ds_read_b128 v[60:63], v211 offset:16384
	ds_read_b128 v[88:91], v211 offset:17408
	ds_read_b128 v[92:95], v211 offset:18432
	ds_read_b128 v[104:107], v211 offset:19456
	ds_read_b128 v[108:111], v211 offset:20480
	ds_read_b128 v[116:119], v211 offset:21504
	ds_read_b128 v[120:123], v211 offset:22528
	ds_read_b128 v[124:127], v211 offset:23552
	global_load_lds_dwordx4 v[128:129], off
	v_lshl_add_u64 v[128:129], v[200:201], 0, s[24:25]
	s_mov_b32 m0, s76
	s_addc_u32 s49, s47, 0
	s_add_i32 s77, s67, s43
	global_load_lds_dwordx4 v[128:129], off
	v_lshl_add_u64 v[128:129], s[48:49], 0, v[176:177]
	s_mov_b32 m0, s77
	s_add_i32 s78, s77, 0x2000
	global_load_lds_dwordx4 v[128:129], off
	v_lshl_add_u64 v[128:129], s[48:49], 0, v[178:179]
	s_mov_b32 m0, s78
	v_lshl_add_u64 v[208:209], s[44:45], 0, v[176:177]
	global_load_lds_dwordx4 v[128:129], off
	v_lshl_add_u64 v[128:129], v[208:209], 0, s[24:25]
	s_mov_b32 m0, s56
	v_lshl_add_u64 v[252:253], s[44:45], 0, v[178:179]
	global_load_lds_dwordx4 v[128:129], off
	v_lshl_add_u64 v[128:129], v[252:253], 0, s[24:25]
	s_mov_b32 m0, s57
	s_nop 0
	global_load_lds_dwordx4 v[128:129], off
	s_waitcnt vmcnt(8)
	s_waitcnt lgkmcnt(0)
	s_barrier
	s_setprio 1
	s_waitcnt lgkmcnt(0)
	v_mfma_f32_16x16x32_bf16 v[134:137], v[20:23], v[60:63], 0
	v_mfma_f32_16x16x32_bf16 v[142:145], v[20:23], v[92:95], 0
	v_mfma_f32_16x16x32_bf16 v[150:153], v[20:23], v[108:111], 0
	v_mfma_f32_16x16x32_bf16 v[20:23], v[20:23], v[120:123], 0
	v_mfma_f32_16x16x32_bf16 v[128:131], v[28:31], v[60:63], 0
	v_mfma_f32_16x16x32_bf16 v[134:137], v[16:19], v[88:91], v[134:137]
	v_mfma_f32_16x16x32_bf16 v[138:141], v[28:31], v[92:95], 0
	v_mfma_f32_16x16x32_bf16 v[142:145], v[16:19], v[104:107], v[142:145]
	v_mfma_f32_16x16x32_bf16 v[146:149], v[28:31], v[108:111], 0
	v_mfma_f32_16x16x32_bf16 v[150:153], v[16:19], v[116:119], v[150:153]
	v_mfma_f32_16x16x32_bf16 v[28:31], v[28:31], v[120:123], 0
	v_mfma_f32_16x16x32_bf16 v[16:19], v[16:19], v[124:127], v[20:23]
	v_mfma_f32_16x16x32_bf16 v[130:133], v[24:27], v[88:91], v[128:131]
	v_mfma_f32_16x16x32_bf16 v[138:141], v[24:27], v[104:107], v[138:141]
	v_mfma_f32_16x16x32_bf16 v[146:149], v[24:27], v[116:119], v[146:149]
	v_mfma_f32_16x16x32_bf16 v[154:157], v[24:27], v[124:127], v[28:31]
	s_setprio 0
	s_setprio 1
	v_mfma_f32_16x16x32_bf16 v[24:27], v[4:7], v[60:63], 0
	v_mfma_f32_16x16x32_bf16 v[158:161], v[0:3], v[88:91], v[24:27]
	v_mfma_f32_16x16x32_bf16 v[24:27], v[12:15], v[92:95], 0
	v_mfma_f32_16x16x32_bf16 v[162:165], v[8:11], v[104:107], v[24:27]
	v_mfma_f32_16x16x32_bf16 v[24:27], v[4:7], v[92:95], 0
	v_mfma_f32_16x16x32_bf16 v[166:169], v[0:3], v[104:107], v[24:27]
	v_mfma_f32_16x16x32_bf16 v[24:27], v[12:15], v[108:111], 0
	v_mfma_f32_16x16x32_bf16 v[20:23], v[12:15], v[60:63], 0
	v_mfma_f32_16x16x32_bf16 v[170:173], v[8:11], v[116:119], v[24:27]
	v_mfma_f32_16x16x32_bf16 v[24:27], v[4:7], v[108:111], 0
	v_mfma_f32_16x16x32_bf16 v[4:7], v[4:7], v[120:123], 0
	v_mfma_f32_16x16x32_bf16 v[20:23], v[8:11], v[88:91], v[20:23]
	v_mfma_f32_16x16x32_bf16 v[190:193], v[0:3], v[116:119], v[24:27]
	v_mfma_f32_16x16x32_bf16 v[12:15], v[12:15], v[120:123], 0
	v_mfma_f32_16x16x32_bf16 v[0:3], v[0:3], v[124:127], v[4:7]
	v_mfma_f32_16x16x32_bf16 v[196:199], v[8:11], v[124:127], v[12:15]
	s_setprio 0
	s_barrier
	s_add_i32 s79, 0, 0x18000
	s_add_i32 s81, 0, 0x1c000
	v_add_u32_e32 v128, s79, v189
	v_add_u32_e32 v129, s81, v189
	ds_read_b128 v[4:7], v128
	ds_read_b128 v[8:11], v128 offset:1024
	ds_read_b128 v[204:207], v128 offset:2048
	ds_read_b128 v[212:215], v128 offset:3072
	ds_read_b128 v[216:219], v129
	ds_read_b128 v[220:223], v129 offset:1024
	ds_read_b128 v[224:227], v129 offset:2048
	ds_read_b128 v[228:231], v129 offset:3072
	s_add_u32 s48, s44, 0x80100
	s_addc_u32 s49, s45, 0
	s_mov_b32 m0, s58
	v_lshl_add_u64 v[88:89], s[48:49], 0, v[176:177]
	ds_read_b128 v[12:15], v211 offset:32768
	ds_read_b128 v[24:27], v211 offset:33792
	ds_read_b128 v[28:31], v211 offset:34816
	ds_read_b128 v[60:63], v211 offset:35840
	ds_read_b128 v[232:235], v211 offset:36864
	ds_read_b128 v[236:239], v211 offset:37888
	ds_read_b128 v[240:243], v211 offset:38912
	ds_read_b128 v[244:247], v211 offset:39936
	global_load_lds_dwordx4 v[88:89], off
	v_lshl_add_u64 v[88:89], s[48:49], 0, v[178:179]
	s_mov_b32 m0, s59
	s_nop 0
	global_load_lds_dwordx4 v[88:89], off
	s_waitcnt vmcnt(8)
	s_waitcnt lgkmcnt(0)
	s_barrier
	s_setprio 1
	s_waitcnt lgkmcnt(0)
	v_mfma_f32_16x16x32_bf16 v[64:67], v[4:7], v[12:15], v[64:67]
	v_mfma_f32_16x16x32_bf16 v[124:127], v[8:11], v[24:27], v[64:67]
	v_mfma_f32_16x16x32_bf16 v[64:67], v[204:207], v[12:15], v[68:71]
	v_mfma_f32_16x16x32_bf16 v[120:123], v[212:215], v[24:27], v[64:67]
	v_mfma_f32_16x16x32_bf16 v[64:67], v[4:7], v[28:31], v[72:75]
	v_mfma_f32_16x16x32_bf16 v[108:111], v[8:11], v[60:63], v[64:67]
	v_mfma_f32_16x16x32_bf16 v[64:67], v[204:207], v[28:31], v[76:79]
	v_mfma_f32_16x16x32_bf16 v[104:107], v[212:215], v[60:63], v[64:67]
	v_mfma_f32_16x16x32_bf16 v[64:67], v[4:7], v[232:235], v[80:83]
	v_mfma_f32_16x16x32_bf16 v[92:95], v[8:11], v[236:239], v[64:67]
	v_mfma_f32_16x16x32_bf16 v[64:67], v[204:207], v[232:235], v[84:87]
	v_mfma_f32_16x16x32_bf16 v[88:91], v[212:215], v[236:239], v[64:67]
	v_mfma_f32_16x16x32_bf16 v[64:67], v[4:7], v[240:243], v[96:99]
	v_mfma_f32_16x16x32_bf16 v[76:79], v[8:11], v[244:247], v[64:67]
	v_mfma_f32_16x16x32_bf16 v[64:67], v[204:207], v[240:243], v[100:103]
	v_mfma_f32_16x16x32_bf16 v[72:75], v[212:215], v[244:247], v[64:67]
	s_setprio 0
	s_setprio 1
	v_mfma_f32_16x16x32_bf16 v[64:67], v[216:219], v[12:15], v[112:115]
	v_mfma_f32_16x16x32_bf16 v[12:15], v[224:227], v[12:15], v[32:35]
	v_mfma_f32_16x16x32_bf16 v[112:115], v[228:231], v[24:27], v[12:15]
	v_mfma_f32_16x16x32_bf16 v[12:15], v[216:219], v[28:31], v[36:39]
	v_mfma_f32_16x16x32_bf16 v[100:103], v[220:223], v[60:63], v[12:15]
	v_mfma_f32_16x16x32_bf16 v[12:15], v[224:227], v[28:31], v[40:43]
	v_mfma_f32_16x16x32_bf16 v[96:99], v[228:231], v[60:63], v[12:15]
	v_mfma_f32_16x16x32_bf16 v[12:15], v[216:219], v[232:235], v[44:47]
	v_mfma_f32_16x16x32_bf16 v[84:87], v[220:223], v[236:239], v[12:15]
	v_mfma_f32_16x16x32_bf16 v[12:15], v[224:227], v[232:235], v[48:51]
	v_mfma_f32_16x16x32_bf16 v[80:83], v[228:231], v[236:239], v[12:15]
	v_mfma_f32_16x16x32_bf16 v[12:15], v[216:219], v[240:243], v[52:55]
	v_mfma_f32_16x16x32_bf16 v[68:71], v[220:223], v[244:247], v[12:15]
	v_mfma_f32_16x16x32_bf16 v[12:15], v[224:227], v[240:243], v[56:59]
	v_mfma_f32_16x16x32_bf16 v[116:119], v[220:223], v[24:27], v[64:67]
	v_mfma_f32_16x16x32_bf16 v[64:67], v[228:231], v[244:247], v[12:15]
	s_setprio 0
	s_barrier
	s_add_i32 s79, s79, s43
	s_add_i32 s80, s79, 0x2000
	s_nop 1
	v_lshl_add_u64 v[12:13], v[174:175], 0, s[26:27]
	s_mov_b32 m0, s79
	s_add_u32 s48, s46, 0x80180
	ds_read_b128 v[32:35], v211 offset:49152
	ds_read_b128 v[36:39], v211 offset:50176
	ds_read_b128 v[232:235], v211 offset:51200
	ds_read_b128 v[236:239], v211 offset:52224
	ds_read_b128 v[240:243], v211 offset:53248
	ds_read_b128 v[244:247], v211 offset:54272
	ds_read_b128 v[248:251], v211 offset:55296
	ds_read_b128 v[184:187], v211 offset:56320
	global_load_lds_dwordx4 v[12:13], off
	v_lshl_add_u64 v[12:13], v[200:201], 0, s[26:27]
	s_mov_b32 m0, s80
	s_addc_u32 s49, s47, 0
	s_add_i32 s81, s81, s43
	global_load_lds_dwordx4 v[12:13], off
	v_lshl_add_u64 v[12:13], s[48:49], 0, v[176:177]
	s_mov_b32 m0, s81
	s_add_i32 s82, s81, 0x2000
	global_load_lds_dwordx4 v[12:13], off
	v_lshl_add_u64 v[12:13], s[48:49], 0, v[178:179]
	s_mov_b32 m0, s82
	s_nop 0
	global_load_lds_dwordx4 v[12:13], off
	v_lshl_add_u64 v[12:13], v[208:209], 0, s[26:27]
	s_mov_b32 m0, s61
	s_nop 0
	global_load_lds_dwordx4 v[12:13], off
	v_lshl_add_u64 v[12:13], v[252:253], 0, s[26:27]
	s_mov_b32 m0, s62
	s_nop 0
	global_load_lds_dwordx4 v[12:13], off
	s_waitcnt vmcnt(8)
	s_waitcnt lgkmcnt(0)
	s_barrier
	s_setprio 1
	s_waitcnt lgkmcnt(0)
	v_mfma_f32_16x16x32_bf16 v[12:15], v[4:7], v[32:35], v[130:133]
	v_mfma_f32_16x16x32_bf16 v[60:63], v[8:11], v[36:39], v[12:15]
	v_mfma_f32_16x16x32_bf16 v[12:15], v[204:207], v[32:35], v[134:137]
	v_mfma_f32_16x16x32_bf16 v[56:59], v[212:215], v[36:39], v[12:15]
	v_mfma_f32_16x16x32_bf16 v[12:15], v[4:7], v[232:235], v[138:141]
	v_mfma_f32_16x16x32_bf16 v[44:47], v[8:11], v[236:239], v[12:15]
	v_mfma_f32_16x16x32_bf16 v[12:15], v[204:207], v[232:235], v[142:145]
	v_mfma_f32_16x16x32_bf16 v[40:43], v[212:215], v[236:239], v[12:15]
	v_mfma_f32_16x16x32_bf16 v[12:15], v[4:7], v[240:243], v[146:149]
	v_mfma_f32_16x16x32_bf16 v[28:31], v[8:11], v[244:247], v[12:15]
	v_mfma_f32_16x16x32_bf16 v[12:15], v[204:207], v[240:243], v[150:153]
	v_mfma_f32_16x16x32_bf16 v[4:7], v[4:7], v[248:251], v[154:157]
	v_mfma_f32_16x16x32_bf16 v[24:27], v[212:215], v[244:247], v[12:15]
	v_mfma_f32_16x16x32_bf16 v[12:15], v[8:11], v[184:187], v[4:7]
	v_mfma_f32_16x16x32_bf16 v[4:7], v[204:207], v[248:251], v[16:19]
	v_mfma_f32_16x16x32_bf16 v[8:11], v[212:215], v[184:187], v[4:7]
	s_setprio 0
	s_setprio 1
	v_mfma_f32_16x16x32_bf16 v[4:7], v[216:219], v[32:35], v[20:23]
	v_mfma_f32_16x16x32_bf16 v[52:55], v[220:223], v[36:39], v[4:7]
	v_mfma_f32_16x16x32_bf16 v[4:7], v[224:227], v[32:35], v[158:161]
	v_mfma_f32_16x16x32_bf16 v[48:51], v[228:231], v[36:39], v[4:7]
	v_mfma_f32_16x16x32_bf16 v[4:7], v[216:219], v[232:235], v[162:165]
	v_mfma_f32_16x16x32_bf16 v[36:39], v[220:223], v[236:239], v[4:7]
	v_mfma_f32_16x16x32_bf16 v[4:7], v[224:227], v[232:235], v[166:169]
	v_mfma_f32_16x16x32_bf16 v[32:35], v[228:231], v[236:239], v[4:7]
	v_mfma_f32_16x16x32_bf16 v[4:7], v[216:219], v[240:243], v[170:173]
	v_mfma_f32_16x16x32_bf16 v[20:23], v[220:223], v[244:247], v[4:7]
	v_mfma_f32_16x16x32_bf16 v[4:7], v[224:227], v[240:243], v[190:193]
	v_mfma_f32_16x16x32_bf16 v[16:19], v[228:231], v[244:247], v[4:7]
	v_mfma_f32_16x16x32_bf16 v[4:7], v[216:219], v[248:251], v[196:199]
	v_mfma_f32_16x16x32_bf16 v[0:3], v[224:227], v[248:251], v[0:3]
	v_mfma_f32_16x16x32_bf16 v[4:7], v[220:223], v[184:187], v[4:7]
	v_mfma_f32_16x16x32_bf16 v[0:3], v[228:231], v[184:187], v[0:3]
	s_setprio 0
	s_barrier
	s_add_u32 s44, s44, 0x80180
	s_addc_u32 s45, s45, 0
	s_add_u32 s83, s46, 0x200
	s_addc_u32 s84, s47, 0
	s_mov_b32 s46, 0
	s_add_i32 s85, s46, 2
	s_and_b32 s47, s85, 6
	s_cmp_lg_u32 s47, 0
	s_cbranch_scc1 .LBB0_700
	s_branch .LBB0_699

.LBB0_783:
	s_ashr_i32 s23, s22, 31
	s_lshl_b64 s[26:27], s[22:23], 19
	s_add_u32 s26, s43, s26
	s_addc_u32 s27, s44, s27
	s_and_b64 s[28:29], s[4:5], exec
	s_cselect_b32 s23, s27, s37
	s_cselect_b32 s31, s26, s36
	s_ashr_i32 s25, s24, 31
	s_lshl_b64 s[28:29], s[24:25], 19
	s_add_u32 s28, s45, s28
	s_addc_u32 s29, s46, s29
	s_and_b64 s[40:41], s[4:5], exec
	s_cselect_b32 s25, s29, s39
	s_cselect_b32 s62, s28, s38
	s_add_u32 s36, s36, 0x40080
	s_addc_u32 s37, s37, 0
	s_add_u32 s63, s38, 0x100
	v_mov_b32_e32 v0, 0
	s_addc_u32 s64, s39, 0
	s_mov_b32 s65, -2
	v_mov_b32_e32 v1, v0
	v_mov_b32_e32 v2, v0
	v_mov_b32_e32 v3, v0
	v_mov_b32_e32 v4, v0
	v_mov_b32_e32 v5, v0
	v_mov_b32_e32 v6, v0
	v_mov_b32_e32 v7, v0
	v_mov_b32_e32 v16, v0
	v_mov_b32_e32 v17, v0
	v_mov_b32_e32 v18, v0
	v_mov_b32_e32 v19, v0
	v_mov_b32_e32 v20, v0
	v_mov_b32_e32 v21, v0
	v_mov_b32_e32 v22, v0
	v_mov_b32_e32 v23, v0
	v_mov_b32_e32 v32, v0
	v_mov_b32_e32 v33, v0
	v_mov_b32_e32 v34, v0
	v_mov_b32_e32 v35, v0
	v_mov_b32_e32 v36, v0
	v_mov_b32_e32 v37, v0
	v_mov_b32_e32 v38, v0
	v_mov_b32_e32 v39, v0
	v_mov_b32_e32 v48, v0
	v_mov_b32_e32 v49, v0
	v_mov_b32_e32 v50, v0
	v_mov_b32_e32 v51, v0
	v_mov_b32_e32 v52, v0
	v_mov_b32_e32 v53, v0
	v_mov_b32_e32 v54, v0
	v_mov_b32_e32 v55, v0
	v_mov_b32_e32 v8, v0
	v_mov_b32_e32 v9, v0
	v_mov_b32_e32 v10, v0
	v_mov_b32_e32 v11, v0
	v_mov_b32_e32 v12, v0
	v_mov_b32_e32 v13, v0
	v_mov_b32_e32 v14, v0
	v_mov_b32_e32 v15, v0
	v_mov_b32_e32 v24, v0
	v_mov_b32_e32 v25, v0
	v_mov_b32_e32 v26, v0
	v_mov_b32_e32 v27, v0
	v_mov_b32_e32 v28, v0
	v_mov_b32_e32 v29, v0
	v_mov_b32_e32 v30, v0
	v_mov_b32_e32 v31, v0
	v_mov_b32_e32 v40, v0
	v_mov_b32_e32 v41, v0
	v_mov_b32_e32 v42, v0
	v_mov_b32_e32 v43, v0
	v_mov_b32_e32 v44, v0
	v_mov_b32_e32 v45, v0
	v_mov_b32_e32 v46, v0
	v_mov_b32_e32 v47, v0
	v_mov_b32_e32 v56, v0
	v_mov_b32_e32 v57, v0
	v_mov_b32_e32 v58, v0
	v_mov_b32_e32 v59, v0
	v_mov_b32_e32 v60, v0
	v_mov_b32_e32 v61, v0
	v_mov_b32_e32 v62, v0
	v_mov_b32_e32 v63, v0
	v_mov_b32_e32 v64, v0
	v_mov_b32_e32 v65, v0
	v_mov_b32_e32 v66, v0
	v_mov_b32_e32 v67, v0
	v_mov_b32_e32 v68, v0
	v_mov_b32_e32 v69, v0
	v_mov_b32_e32 v70, v0
	v_mov_b32_e32 v71, v0
	v_mov_b32_e32 v80, v0
	v_mov_b32_e32 v81, v0
	v_mov_b32_e32 v82, v0
	v_mov_b32_e32 v83, v0
	v_mov_b32_e32 v84, v0
	v_mov_b32_e32 v85, v0
	v_mov_b32_e32 v86, v0
	v_mov_b32_e32 v87, v0
	v_mov_b32_e32 v96, v0
	v_mov_b32_e32 v97, v0
	v_mov_b32_e32 v98, v0
	v_mov_b32_e32 v99, v0
	v_mov_b32_e32 v100, v0
	v_mov_b32_e32 v101, v0
	v_mov_b32_e32 v102, v0
	v_mov_b32_e32 v103, v0
	v_mov_b32_e32 v112, v0
	v_mov_b32_e32 v113, v0
	v_mov_b32_e32 v114, v0
	v_mov_b32_e32 v115, v0
	v_mov_b32_e32 v116, v0
	v_mov_b32_e32 v117, v0
	v_mov_b32_e32 v118, v0
	v_mov_b32_e32 v119, v0
	v_mov_b32_e32 v72, v0
	v_mov_b32_e32 v73, v0
	v_mov_b32_e32 v74, v0
	v_mov_b32_e32 v75, v0
	v_mov_b32_e32 v76, v0
	v_mov_b32_e32 v77, v0
	v_mov_b32_e32 v78, v0
	v_mov_b32_e32 v79, v0
	v_mov_b32_e32 v88, v0
	v_mov_b32_e32 v89, v0
	v_mov_b32_e32 v90, v0
	v_mov_b32_e32 v91, v0
	v_mov_b32_e32 v92, v0
	v_mov_b32_e32 v93, v0
	v_mov_b32_e32 v94, v0
	v_mov_b32_e32 v95, v0
	v_mov_b32_e32 v104, v0
	v_mov_b32_e32 v105, v0
	v_mov_b32_e32 v106, v0
	v_mov_b32_e32 v107, v0
	v_mov_b32_e32 v108, v0
	v_mov_b32_e32 v109, v0
	v_mov_b32_e32 v110, v0
	v_mov_b32_e32 v111, v0
	v_mov_b32_e32 v120, v0
	v_mov_b32_e32 v121, v0
	v_mov_b32_e32 v122, v0
	v_mov_b32_e32 v123, v0
	v_mov_b32_e32 v124, v0
	v_mov_b32_e32 v125, v0
	v_mov_b32_e32 v126, v0
	v_mov_b32_e32 v127, v0

.LBB0_865:
	s_add_u32 s62, s28, 0x100
	v_mov_b32_e32 v0, 0
	s_addc_u32 s63, s29, 0
	s_mov_b32 s64, -2
	v_mov_b32_e32 v1, v0
	v_mov_b32_e32 v2, v0
	v_mov_b32_e32 v3, v0
	v_mov_b32_e32 v4, v0
	v_mov_b32_e32 v5, v0
	v_mov_b32_e32 v6, v0
	v_mov_b32_e32 v7, v0
	v_mov_b32_e32 v16, v0
	v_mov_b32_e32 v17, v0
	v_mov_b32_e32 v18, v0
	v_mov_b32_e32 v19, v0
	v_mov_b32_e32 v20, v0
	v_mov_b32_e32 v21, v0
	v_mov_b32_e32 v22, v0
	v_mov_b32_e32 v23, v0
	v_mov_b32_e32 v32, v0
	v_mov_b32_e32 v33, v0
	v_mov_b32_e32 v34, v0
	v_mov_b32_e32 v35, v0
	v_mov_b32_e32 v36, v0
	v_mov_b32_e32 v37, v0
	v_mov_b32_e32 v38, v0
	v_mov_b32_e32 v39, v0
	v_mov_b32_e32 v48, v0
	v_mov_b32_e32 v49, v0
	v_mov_b32_e32 v50, v0
	v_mov_b32_e32 v51, v0
	v_mov_b32_e32 v52, v0
	v_mov_b32_e32 v53, v0
	v_mov_b32_e32 v54, v0
	v_mov_b32_e32 v55, v0
	v_mov_b32_e32 v8, v0
	v_mov_b32_e32 v9, v0
	v_mov_b32_e32 v10, v0
	v_mov_b32_e32 v11, v0
	v_mov_b32_e32 v12, v0
	v_mov_b32_e32 v13, v0
	v_mov_b32_e32 v14, v0
	v_mov_b32_e32 v15, v0
	v_mov_b32_e32 v24, v0
	v_mov_b32_e32 v25, v0
	v_mov_b32_e32 v26, v0
	v_mov_b32_e32 v27, v0
	v_mov_b32_e32 v28, v0
	v_mov_b32_e32 v29, v0
	v_mov_b32_e32 v30, v0
	v_mov_b32_e32 v31, v0
	v_mov_b32_e32 v40, v0
	v_mov_b32_e32 v41, v0
	v_mov_b32_e32 v42, v0
	v_mov_b32_e32 v43, v0
	v_mov_b32_e32 v44, v0
	v_mov_b32_e32 v45, v0
	v_mov_b32_e32 v46, v0
	v_mov_b32_e32 v47, v0
	v_mov_b32_e32 v56, v0
	v_mov_b32_e32 v57, v0
	v_mov_b32_e32 v58, v0
	v_mov_b32_e32 v59, v0
	v_mov_b32_e32 v60, v0
	v_mov_b32_e32 v61, v0
	v_mov_b32_e32 v62, v0
	v_mov_b32_e32 v63, v0
	v_mov_b32_e32 v64, v0
	v_mov_b32_e32 v65, v0
	v_mov_b32_e32 v66, v0
	v_mov_b32_e32 v67, v0
	v_mov_b32_e32 v68, v0
	v_mov_b32_e32 v69, v0
	v_mov_b32_e32 v70, v0
	v_mov_b32_e32 v71, v0
	v_mov_b32_e32 v80, v0
	v_mov_b32_e32 v81, v0
	v_mov_b32_e32 v82, v0
	v_mov_b32_e32 v83, v0
	v_mov_b32_e32 v84, v0
	v_mov_b32_e32 v85, v0
	v_mov_b32_e32 v86, v0
	v_mov_b32_e32 v87, v0
	v_mov_b32_e32 v96, v0
	v_mov_b32_e32 v97, v0
	v_mov_b32_e32 v98, v0
	v_mov_b32_e32 v99, v0
	v_mov_b32_e32 v100, v0
	v_mov_b32_e32 v101, v0
	v_mov_b32_e32 v102, v0
	v_mov_b32_e32 v103, v0
	v_mov_b32_e32 v112, v0
	v_mov_b32_e32 v113, v0
	v_mov_b32_e32 v114, v0
	v_mov_b32_e32 v115, v0
	v_mov_b32_e32 v116, v0
	v_mov_b32_e32 v117, v0
	v_mov_b32_e32 v118, v0
	v_mov_b32_e32 v119, v0
	v_mov_b32_e32 v72, v0
	v_mov_b32_e32 v73, v0
	v_mov_b32_e32 v74, v0
	v_mov_b32_e32 v75, v0
	v_mov_b32_e32 v76, v0
	v_mov_b32_e32 v77, v0
	v_mov_b32_e32 v78, v0
	v_mov_b32_e32 v79, v0
	v_mov_b32_e32 v88, v0
	v_mov_b32_e32 v89, v0
	v_mov_b32_e32 v90, v0
	v_mov_b32_e32 v91, v0
	v_mov_b32_e32 v92, v0
	v_mov_b32_e32 v93, v0
	v_mov_b32_e32 v94, v0
	v_mov_b32_e32 v95, v0
	v_mov_b32_e32 v104, v0
	v_mov_b32_e32 v105, v0
	v_mov_b32_e32 v106, v0
	v_mov_b32_e32 v107, v0
	v_mov_b32_e32 v108, v0
	v_mov_b32_e32 v109, v0
	v_mov_b32_e32 v110, v0
	v_mov_b32_e32 v111, v0
	v_mov_b32_e32 v128, v0
	v_mov_b32_e32 v129, v0
	v_mov_b32_e32 v130, v0
	v_mov_b32_e32 v131, v0
	v_mov_b32_e32 v132, v0
	v_mov_b32_e32 v133, v0
	v_mov_b32_e32 v134, v0
	v_mov_b32_e32 v135, v0

.LBB0_951:
	s_ashr_i32 s27, s26, 31
	s_lshl_b64 s[30:31], s[26:27], 19
	s_add_u32 s30, s47, s30
	s_addc_u32 s31, s48, s31
	s_and_b64 s[36:37], s[4:5], exec
	s_cselect_b32 s27, s31, s7
	s_cselect_b32 s39, s30, s6
	s_ashr_i32 s29, s28, 31
	s_lshl_b64 s[36:37], s[28:29], 19
	s_add_u32 s36, s49, s36
	s_addc_u32 s37, s50, s37
	s_and_b64 s[44:45], s[4:5], exec
	s_cselect_b32 s29, s37, s41
	s_cselect_b32 s43, s36, s40
	s_add_u32 s6, s6, 0x40080
	s_addc_u32 s7, s7, 0
	s_add_u32 s71, s40, 0x100
	v_mov_b32_e32 v0, 0
	s_addc_u32 s72, s41, 0
	s_mov_b32 s73, -2
	v_mov_b32_e32 v1, v0
	v_mov_b32_e32 v2, v0
	v_mov_b32_e32 v3, v0
	v_mov_b32_e32 v4, v0
	v_mov_b32_e32 v5, v0
	v_mov_b32_e32 v6, v0
	v_mov_b32_e32 v7, v0
	v_mov_b32_e32 v16, v0
	v_mov_b32_e32 v17, v0
	v_mov_b32_e32 v18, v0
	v_mov_b32_e32 v19, v0
	v_mov_b32_e32 v20, v0
	v_mov_b32_e32 v21, v0
	v_mov_b32_e32 v22, v0
	v_mov_b32_e32 v23, v0
	v_mov_b32_e32 v32, v0
	v_mov_b32_e32 v33, v0
	v_mov_b32_e32 v34, v0
	v_mov_b32_e32 v35, v0
	v_mov_b32_e32 v36, v0
	v_mov_b32_e32 v37, v0
	v_mov_b32_e32 v38, v0
	v_mov_b32_e32 v39, v0
	v_mov_b32_e32 v48, v0
	v_mov_b32_e32 v49, v0
	v_mov_b32_e32 v50, v0
	v_mov_b32_e32 v51, v0
	v_mov_b32_e32 v52, v0
	v_mov_b32_e32 v53, v0
	v_mov_b32_e32 v54, v0
	v_mov_b32_e32 v55, v0
	v_mov_b32_e32 v8, v0
	v_mov_b32_e32 v9, v0
	v_mov_b32_e32 v10, v0
	v_mov_b32_e32 v11, v0
	v_mov_b32_e32 v12, v0
	v_mov_b32_e32 v13, v0
	v_mov_b32_e32 v14, v0
	v_mov_b32_e32 v15, v0
	v_mov_b32_e32 v24, v0
	v_mov_b32_e32 v25, v0
	v_mov_b32_e32 v26, v0
	v_mov_b32_e32 v27, v0
	v_mov_b32_e32 v28, v0
	v_mov_b32_e32 v29, v0
	v_mov_b32_e32 v30, v0
	v_mov_b32_e32 v31, v0
	v_mov_b32_e32 v40, v0
	v_mov_b32_e32 v41, v0
	v_mov_b32_e32 v42, v0
	v_mov_b32_e32 v43, v0
	v_mov_b32_e32 v44, v0
	v_mov_b32_e32 v45, v0
	v_mov_b32_e32 v46, v0
	v_mov_b32_e32 v47, v0
	v_mov_b32_e32 v56, v0
	v_mov_b32_e32 v57, v0
	v_mov_b32_e32 v58, v0
	v_mov_b32_e32 v59, v0
	v_mov_b32_e32 v60, v0
	v_mov_b32_e32 v61, v0
	v_mov_b32_e32 v62, v0
	v_mov_b32_e32 v63, v0
	v_mov_b32_e32 v64, v0
	v_mov_b32_e32 v65, v0
	v_mov_b32_e32 v66, v0
	v_mov_b32_e32 v67, v0
	v_mov_b32_e32 v68, v0
	v_mov_b32_e32 v69, v0
	v_mov_b32_e32 v70, v0
	v_mov_b32_e32 v71, v0
	v_mov_b32_e32 v80, v0
	v_mov_b32_e32 v81, v0
	v_mov_b32_e32 v82, v0
	v_mov_b32_e32 v83, v0
	v_mov_b32_e32 v84, v0
	v_mov_b32_e32 v85, v0
	v_mov_b32_e32 v86, v0
	v_mov_b32_e32 v87, v0
	v_mov_b32_e32 v96, v0
	v_mov_b32_e32 v97, v0
	v_mov_b32_e32 v98, v0
	v_mov_b32_e32 v99, v0
	v_mov_b32_e32 v100, v0
	v_mov_b32_e32 v101, v0
	v_mov_b32_e32 v102, v0
	v_mov_b32_e32 v103, v0
	v_mov_b32_e32 v112, v0
	v_mov_b32_e32 v113, v0
	v_mov_b32_e32 v114, v0
	v_mov_b32_e32 v115, v0
	v_mov_b32_e32 v116, v0
	v_mov_b32_e32 v117, v0
	v_mov_b32_e32 v118, v0
	v_mov_b32_e32 v119, v0
	v_mov_b32_e32 v72, v0
	v_mov_b32_e32 v73, v0
	v_mov_b32_e32 v74, v0
	v_mov_b32_e32 v75, v0
	v_mov_b32_e32 v76, v0
	v_mov_b32_e32 v77, v0
	v_mov_b32_e32 v78, v0
	v_mov_b32_e32 v79, v0
	v_mov_b32_e32 v88, v0
	v_mov_b32_e32 v89, v0
	v_mov_b32_e32 v90, v0
	v_mov_b32_e32 v91, v0
	v_mov_b32_e32 v92, v0
	v_mov_b32_e32 v93, v0
	v_mov_b32_e32 v94, v0
	v_mov_b32_e32 v95, v0
	v_mov_b32_e32 v104, v0
	v_mov_b32_e32 v105, v0
	v_mov_b32_e32 v106, v0
	v_mov_b32_e32 v107, v0
	v_mov_b32_e32 v108, v0
	v_mov_b32_e32 v109, v0
	v_mov_b32_e32 v110, v0
	v_mov_b32_e32 v111, v0
	v_mov_b32_e32 v120, v0
	v_mov_b32_e32 v121, v0
	v_mov_b32_e32 v122, v0
	v_mov_b32_e32 v123, v0
	v_mov_b32_e32 v124, v0
	v_mov_b32_e32 v125, v0
	v_mov_b32_e32 v126, v0
	v_mov_b32_e32 v127, v0

.LBB0_1145:
	s_ashr_i32 s23, s22, 31
	s_lshl_b64 s[26:27], s[22:23], 19
	s_add_u32 s26, s45, s26
	s_addc_u32 s27, s46, s27
	s_and_b64 s[28:29], s[4:5], exec
	s_cselect_b32 s23, s27, s39
	s_cselect_b32 s31, s26, s38
	s_ashr_i32 s25, s24, 31
	s_lshl_b64 s[28:29], s[24:25], 19
	s_add_u32 s28, s47, s28
	s_addc_u32 s29, s48, s29
	s_and_b64 s[42:43], s[4:5], exec
	s_cselect_b32 s25, s29, s41
	s_cselect_b32 s37, s28, s40
	s_add_u32 s38, s38, 0x40080
	s_addc_u32 s39, s39, 0
	s_add_u32 s64, s40, 0x100
	v_mov_b32_e32 v0, 0
	s_addc_u32 s65, s41, 0
	s_mov_b32 s66, -2
	v_mov_b32_e32 v1, v0
	v_mov_b32_e32 v2, v0
	v_mov_b32_e32 v3, v0
	v_mov_b32_e32 v4, v0
	v_mov_b32_e32 v5, v0
	v_mov_b32_e32 v6, v0
	v_mov_b32_e32 v7, v0
	v_mov_b32_e32 v16, v0
	v_mov_b32_e32 v17, v0
	v_mov_b32_e32 v18, v0
	v_mov_b32_e32 v19, v0
	v_mov_b32_e32 v20, v0
	v_mov_b32_e32 v21, v0
	v_mov_b32_e32 v22, v0
	v_mov_b32_e32 v23, v0
	v_mov_b32_e32 v32, v0
	v_mov_b32_e32 v33, v0
	v_mov_b32_e32 v34, v0
	v_mov_b32_e32 v35, v0
	v_mov_b32_e32 v36, v0
	v_mov_b32_e32 v37, v0
	v_mov_b32_e32 v38, v0
	v_mov_b32_e32 v39, v0
	v_mov_b32_e32 v48, v0
	v_mov_b32_e32 v49, v0
	v_mov_b32_e32 v50, v0
	v_mov_b32_e32 v51, v0
	v_mov_b32_e32 v52, v0
	v_mov_b32_e32 v53, v0
	v_mov_b32_e32 v54, v0
	v_mov_b32_e32 v55, v0
	v_mov_b32_e32 v8, v0
	v_mov_b32_e32 v9, v0
	v_mov_b32_e32 v10, v0
	v_mov_b32_e32 v11, v0
	v_mov_b32_e32 v12, v0
	v_mov_b32_e32 v13, v0
	v_mov_b32_e32 v14, v0
	v_mov_b32_e32 v15, v0
	v_mov_b32_e32 v24, v0
	v_mov_b32_e32 v25, v0
	v_mov_b32_e32 v26, v0
	v_mov_b32_e32 v27, v0
	v_mov_b32_e32 v28, v0
	v_mov_b32_e32 v29, v0
	v_mov_b32_e32 v30, v0
	v_mov_b32_e32 v31, v0
	v_mov_b32_e32 v40, v0
	v_mov_b32_e32 v41, v0
	v_mov_b32_e32 v42, v0
	v_mov_b32_e32 v43, v0
	v_mov_b32_e32 v44, v0
	v_mov_b32_e32 v45, v0
	v_mov_b32_e32 v46, v0
	v_mov_b32_e32 v47, v0
	v_mov_b32_e32 v56, v0
	v_mov_b32_e32 v57, v0
	v_mov_b32_e32 v58, v0
	v_mov_b32_e32 v59, v0
	v_mov_b32_e32 v60, v0
	v_mov_b32_e32 v61, v0
	v_mov_b32_e32 v62, v0
	v_mov_b32_e32 v63, v0
	v_mov_b32_e32 v64, v0
	v_mov_b32_e32 v65, v0
	v_mov_b32_e32 v66, v0
	v_mov_b32_e32 v67, v0
	v_mov_b32_e32 v68, v0
	v_mov_b32_e32 v69, v0
	v_mov_b32_e32 v70, v0
	v_mov_b32_e32 v71, v0
	v_mov_b32_e32 v80, v0
	v_mov_b32_e32 v81, v0
	v_mov_b32_e32 v82, v0
	v_mov_b32_e32 v83, v0
	v_mov_b32_e32 v84, v0
	v_mov_b32_e32 v85, v0
	v_mov_b32_e32 v86, v0
	v_mov_b32_e32 v87, v0
	v_mov_b32_e32 v96, v0
	v_mov_b32_e32 v97, v0
	v_mov_b32_e32 v98, v0
	v_mov_b32_e32 v99, v0
	v_mov_b32_e32 v100, v0
	v_mov_b32_e32 v101, v0
	v_mov_b32_e32 v102, v0
	v_mov_b32_e32 v103, v0
	v_mov_b32_e32 v112, v0
	v_mov_b32_e32 v113, v0
	v_mov_b32_e32 v114, v0
	v_mov_b32_e32 v115, v0
	v_mov_b32_e32 v116, v0
	v_mov_b32_e32 v117, v0
	v_mov_b32_e32 v118, v0
	v_mov_b32_e32 v119, v0
	v_mov_b32_e32 v72, v0
	v_mov_b32_e32 v73, v0
	v_mov_b32_e32 v74, v0
	v_mov_b32_e32 v75, v0
	v_mov_b32_e32 v76, v0
	v_mov_b32_e32 v77, v0
	v_mov_b32_e32 v78, v0
	v_mov_b32_e32 v79, v0
	v_mov_b32_e32 v88, v0
	v_mov_b32_e32 v89, v0
	v_mov_b32_e32 v90, v0
	v_mov_b32_e32 v91, v0
	v_mov_b32_e32 v92, v0
	v_mov_b32_e32 v93, v0
	v_mov_b32_e32 v94, v0
	v_mov_b32_e32 v95, v0
	v_mov_b32_e32 v104, v0
	v_mov_b32_e32 v105, v0
	v_mov_b32_e32 v106, v0
	v_mov_b32_e32 v107, v0
	v_mov_b32_e32 v108, v0
	v_mov_b32_e32 v109, v0
	v_mov_b32_e32 v110, v0
	v_mov_b32_e32 v111, v0
	v_mov_b32_e32 v124, v0
	v_mov_b32_e32 v125, v0
	v_mov_b32_e32 v126, v0
	v_mov_b32_e32 v127, v0
	v_mov_b32_e32 v128, v0
	v_mov_b32_e32 v129, v0
	v_mov_b32_e32 v130, v0
	v_mov_b32_e32 v131, v0

.LBB0_1309:
	s_add_u32 s51, s26, 0x100
	v_mov_b32_e32 v4, 0
	s_addc_u32 s52, s27, 0
	s_mov_b32 s53, -2
	v_mov_b32_e32 v5, v4
	v_mov_b32_e32 v6, v4
	v_mov_b32_e32 v7, v4
	v_mov_b32_e32 v0, v4
	v_mov_b32_e32 v1, v4
	v_mov_b32_e32 v2, v4
	v_mov_b32_e32 v3, v4
	v_mov_b32_e32 v20, v4
	v_mov_b32_e32 v21, v4
	v_mov_b32_e32 v22, v4
	v_mov_b32_e32 v23, v4
	v_mov_b32_e32 v16, v4
	v_mov_b32_e32 v17, v4
	v_mov_b32_e32 v18, v4
	v_mov_b32_e32 v19, v4
	v_mov_b32_e32 v36, v4
	v_mov_b32_e32 v37, v4
	v_mov_b32_e32 v38, v4
	v_mov_b32_e32 v39, v4
	v_mov_b32_e32 v32, v4
	v_mov_b32_e32 v33, v4
	v_mov_b32_e32 v34, v4
	v_mov_b32_e32 v35, v4
	v_mov_b32_e32 v52, v4
	v_mov_b32_e32 v53, v4
	v_mov_b32_e32 v54, v4
	v_mov_b32_e32 v55, v4
	v_mov_b32_e32 v48, v4
	v_mov_b32_e32 v49, v4
	v_mov_b32_e32 v50, v4
	v_mov_b32_e32 v51, v4
	v_mov_b32_e32 v12, v4
	v_mov_b32_e32 v13, v4
	v_mov_b32_e32 v14, v4
	v_mov_b32_e32 v15, v4
	v_mov_b32_e32 v8, v4
	v_mov_b32_e32 v9, v4
	v_mov_b32_e32 v10, v4
	v_mov_b32_e32 v11, v4
	v_mov_b32_e32 v28, v4
	v_mov_b32_e32 v29, v4
	v_mov_b32_e32 v30, v4
	v_mov_b32_e32 v31, v4
	v_mov_b32_e32 v24, v4
	v_mov_b32_e32 v25, v4
	v_mov_b32_e32 v26, v4
	v_mov_b32_e32 v27, v4
	v_mov_b32_e32 v44, v4
	v_mov_b32_e32 v45, v4
	v_mov_b32_e32 v46, v4
	v_mov_b32_e32 v47, v4
	v_mov_b32_e32 v40, v4
	v_mov_b32_e32 v41, v4
	v_mov_b32_e32 v42, v4
	v_mov_b32_e32 v43, v4
	v_mov_b32_e32 v60, v4
	v_mov_b32_e32 v61, v4
	v_mov_b32_e32 v62, v4
	v_mov_b32_e32 v63, v4
	v_mov_b32_e32 v56, v4
	v_mov_b32_e32 v57, v4
	v_mov_b32_e32 v58, v4
	v_mov_b32_e32 v59, v4
	v_mov_b32_e32 v68, v4
	v_mov_b32_e32 v69, v4
	v_mov_b32_e32 v70, v4
	v_mov_b32_e32 v71, v4
	v_mov_b32_e32 v64, v4
	v_mov_b32_e32 v65, v4
	v_mov_b32_e32 v66, v4
	v_mov_b32_e32 v67, v4
	v_mov_b32_e32 v84, v4
	v_mov_b32_e32 v85, v4
	v_mov_b32_e32 v86, v4
	v_mov_b32_e32 v87, v4
	v_mov_b32_e32 v80, v4
	v_mov_b32_e32 v81, v4
	v_mov_b32_e32 v82, v4
	v_mov_b32_e32 v83, v4
	v_mov_b32_e32 v92, v4
	v_mov_b32_e32 v93, v4
	v_mov_b32_e32 v94, v4
	v_mov_b32_e32 v95, v4
	v_mov_b32_e32 v96, v4
	v_mov_b32_e32 v97, v4
	v_mov_b32_e32 v98, v4
	v_mov_b32_e32 v99, v4
	v_mov_b32_e32 v104, v4
	v_mov_b32_e32 v105, v4
	v_mov_b32_e32 v106, v4
	v_mov_b32_e32 v107, v4
	v_mov_b32_e32 v112, v4
	v_mov_b32_e32 v113, v4
	v_mov_b32_e32 v114, v4
	v_mov_b32_e32 v115, v4
	v_mov_b32_e32 v76, v4
	v_mov_b32_e32 v77, v4
	v_mov_b32_e32 v78, v4
	v_mov_b32_e32 v79, v4
	v_mov_b32_e32 v72, v4
	v_mov_b32_e32 v73, v4
	v_mov_b32_e32 v74, v4
	v_mov_b32_e32 v75, v4
	v_mov_b32_e32 v100, v4
	v_mov_b32_e32 v101, v4
	v_mov_b32_e32 v102, v4
	v_mov_b32_e32 v103, v4
	v_mov_b32_e32 v88, v4
	v_mov_b32_e32 v89, v4
	v_mov_b32_e32 v90, v4
	v_mov_b32_e32 v91, v4
	v_mov_b32_e32 v108, v4
	v_mov_b32_e32 v109, v4
	v_mov_b32_e32 v110, v4
	v_mov_b32_e32 v111, v4
	v_mov_b32_e32 v116, v4
	v_mov_b32_e32 v117, v4
	v_mov_b32_e32 v118, v4
	v_mov_b32_e32 v119, v4
	v_mov_b32_e32 v120, v4
	v_mov_b32_e32 v121, v4
	v_mov_b32_e32 v122, v4
	v_mov_b32_e32 v123, v4
	v_mov_b32_e32 v124, v4
	v_mov_b32_e32 v125, v4
	v_mov_b32_e32 v126, v4
	v_mov_b32_e32 v127, v4
